# v11 + removed redundant max(x,x) canonicalisation in the slc attention loops
# speedup vs baseline: 1.0008x; 1.0008x over previous
; DEVI void attn_item(const Params& p, int bg, int t0, unsigned char* smem) {
;     ...
;         if (is_slc && !elem) {
;             const unsigned aw = __builtin_amdgcn_readfirstlane(anyw[jt >> 5] | anyw[4 + (jt >> 5)]);
;             any_act = (aw >> (jt & 31)) & 1u;
;         }
;         if (any_act) {
;             f32x4 s[2][4];
;             {
;                 bf16x8 k0[4], k1[4];
; #pragma unroll
;                 for (int mt = 0; mt < 4; ++mt) {
;                     k0[mt] = *(const bf16x8*)(cK + (mt * 16 + l16) * 128 + ((quad ^ rsw) * 16));
;                     k1[mt] = *(const bf16x8*)(cK + (mt * 16 + l16) * 128 + (((4 + quad) ^ rsw) * 16));
;                 }
; #pragma unroll
;                 for (int mt = 0; mt < 4; ++mt)
; #pragma unroll
;                     for (int ct = 0; ct < 2; ++ct) s[ct][mt] = mfma16(k0[mt], qf[ct][0], (f32x4){0.f, 0.f, 0.f, 0.f});
; #pragma unroll
;                 for (int mt = 0; mt < 4; ++mt)
; #pragma unroll
;                     for (int ct = 0; ct < 2; ++ct) s[ct][mt] = mfma16(k1[mt], qf[ct][1], s[ct][mt]);
;     ...
; #pragma unroll
;                         for (int ct = 0; ct < 2; ++ct) {
;                             mr[ct] = fmaxf(fmaxf(s[ct][0][0], s[ct][0][1]), fmaxf(s[ct][0][2], s[ct][0][3]));
; #pragma unroll
;                             for (int mt = 1; mt < 4; ++mt) mr[ct] = fmaxf(mr[ct], fmaxf(fmaxf(s[ct][mt][0], s[ct][mt][1]), fmaxf(s[ct][mt][2], s[ct][mt][3])));
;                         }
; #pragma unroll
;                         for (int ct = 0; ct < 2; ++ct) mr[ct] = rmax16(mr[ct]);
; #pragma unroll
;                         for (int ct = 0; ct < 2; ++ct) mr[ct] = rmax32(mr[ct]);
;                         float cand[2];
;                         bool need = false;
; #pragma unroll
;                         for (int ct = 0; ct < 2; ++ct) {
;                             cand[ct] = fmaxf(m[ct], __builtin_fmaf(mr[ct], LOG2E, bias[ct]));
;                             need = need || (cand[ct] - m[ct] > 8.0f);
;                         }
;                         const bool resc = __builtin_amdgcn_ballot_w64(need) != 0;
; #pragma unroll
;                         for (int ct = 0; ct < 2; ++ct) {
;                             mn[ct] = resc ? cand[ct] : m[ct];
;                             const float nb = bias[ct] - mn[ct];
; #pragma unroll
;                             for (int mt = 0; mt < 4; ++mt)
.LBB0_502:
	s_add_i32 s0, s70, s13
	s_ashr_i32 s1, s0, 5
	s_lshl_b32 s13, s1, 2
	s_add_i32 s13, s10, s13
	v_mov_b32_e32 v0, s13
	v_add_u32_e32 v0, 0xa000, v0
	ds_read2_b32 v[92:93], v0 offset0:32 offset1:36
	s_lshl_b32 s0, 1, s0
	s_waitcnt lgkmcnt(0)
	v_or_b32_e32 v0, v93, v92
	s_nop 0
	v_readfirstlane_b32 s13, v0
	s_and_b32 s13, s13, s0
	s_cmp_eq_u32 s13, 0
	s_cbranch_scc1 .LBB0_490
	s_and_b32 s13, s71, 0x4000
	v_or_b32_e32 v171, s13, v160
	v_add_u32_e32 v0, v171, v161
	ds_read_b128 v[92:95], v0
	v_add_u32_e32 v2, v171, v162
	ds_read_b128 v[96:99], v2
	ds_read_b128 v[100:103], v0 offset:2048
	ds_read_b128 v[108:111], v2 offset:2048
	ds_read_b128 v[104:107], v0 offset:4096
	ds_read_b128 v[172:175], v2 offset:4096
	ds_read_b128 v[112:115], v0 offset:6144
	ds_read_b128 v[176:179], v2 offset:6144
	s_waitcnt vmcnt(5) lgkmcnt(3)
	v_mfma_f32_16x16x32_bf16 v[184:187], v[104:107], v[4:7], 0
	v_lshl_add_u32 v0, s1, 2, v170
	v_add_u32_e32 v0, 0xa000, v0
	s_waitcnt vmcnt(2)
	v_mfma_f32_16x16x32_bf16 v[188:191], v[104:107], v[12:15], 0
	v_mfma_f32_16x16x32_bf16 v[116:119], v[92:95], v[4:7], 0
	v_mfma_f32_16x16x32_bf16 v[92:95], v[92:95], v[12:15], 0
	s_waitcnt lgkmcnt(1)
	v_mfma_f32_16x16x32_bf16 v[192:195], v[112:115], v[4:7], 0
	v_mfma_f32_16x16x32_bf16 v[196:199], v[112:115], v[12:15], 0
	v_mfma_f32_16x16x32_bf16 v[120:123], v[96:99], v[8:11], v[116:119]
	s_waitcnt vmcnt(1)
	v_mfma_f32_16x16x32_bf16 v[104:107], v[96:99], v[16:19], v[92:95]
	v_mfma_f32_16x16x32_bf16 v[112:115], v[172:175], v[8:11], v[184:187]
	s_nop 4
	v_mfma_f32_16x16x32_bf16 v[96:99], v[172:175], v[16:19], v[188:191]
	ds_read2_b32 v[174:175], v0 offset1:16
	s_waitcnt lgkmcnt(0)
	v_and_b32_e32 v0, s0, v174
	v_mfma_f32_16x16x32_bf16 v[180:183], v[100:103], v[4:7], 0
	v_cmp_eq_u32_e32 vcc, 0, v0
	v_and_b32_e32 v0, s0, v175
	v_mfma_f32_16x16x32_bf16 v[100:103], v[100:103], v[12:15], 0
	v_cndmask_b32_e32 v173, 0, v147, vcc
	v_cmp_eq_u32_e32 vcc, 0, v0
	v_mfma_f32_16x16x32_bf16 v[116:119], v[108:111], v[8:11], v[180:183]
	v_max_f32_e32 v0, v120, v121
	v_max_f32_e32 v2, v122, v123
	v_mfma_f32_16x16x32_bf16 v[100:103], v[108:111], v[16:19], v[100:103]
	v_cndmask_b32_e32 v172, 0, v147, vcc
	s_nop 2
	v_mfma_f32_16x16x32_bf16 v[108:111], v[176:179], v[8:11], v[192:195]
	v_max_f32_e32 v167, v118, v119
	v_max3_f32 v167, v116, v117, v167
	v_max3_f32 v0, v0, v2, v167
	v_max_f32_e32 v2, v114, v115
	s_nop 1
	v_max_f32_e32 v167, v110, v111
	v_max3_f32 v2, v112, v113, v2
	v_max3_f32 v167, v108, v109, v167
	v_max3_f32 v0, v0, v2, v167
	v_max_f32_e32 v2, v104, v105
	v_mfma_f32_16x16x32_bf16 v[92:95], v[176:179], v[16:19], v[196:199]
	v_max_f32_e32 v167, v106, v107
	v_max_f32_e32 v168, v102, v103
	v_max3_f32 v168, v100, v101, v168
	v_max3_f32 v2, v2, v167, v168
	v_max_f32_e32 v167, v98, v99
	v_max_f32_e32 v174, v94, v94
	v_max_f32_e32 v168, v174, v95
	v_max3_f32 v167, v96, v97, v167
	v_max3_f32 v168, v92, v93, v168
	v_max3_f32 v2, v2, v167, v168
	v_mov_b32_e32 v167, v0
	s_nop 1
	v_permlane16_swap_b32_e32 v0, v167
	v_max_f32_e32 v167, v167, v167
	v_max_f32_e32 v0, v0, v0
	v_max_f32_e32 v0, v0, v167
	v_mov_b32_e32 v167, v2
	s_nop 1
	v_permlane16_swap_b32_e32 v2, v167
	v_max_f32_e32 v167, v167, v167
	v_max_f32_e32 v2, v2, v2
	v_max_f32_e32 v2, v2, v167
	v_mov_b32_e32 v167, v0
	s_nop 1
	v_permlane32_swap_b32_e32 v0, v167
	v_max_f32_e32 v167, v167, v167
	v_max_f32_e32 v0, v0, v0
	v_max_f32_e32 v0, v0, v167
	v_mov_b32_e32 v167, v2
	s_nop 1
	v_permlane32_swap_b32_e32 v2, v167
	v_max_f32_e32 v167, v167, v167
	v_max_f32_e32 v2, v2, v2
	v_max_f32_e32 v2, v2, v167
	v_fmamk_f32 v0, v0, 0x3fb8aa3b, v173
	v_fmamk_f32 v2, v2, 0x3fb8aa3b, v172
	v_max_f32_e32 v0, v166, v0
	v_max_f32_e32 v2, v165, v2
	v_sub_f32_e32 v167, v0, v166
	v_sub_f32_e32 v168, v2, v165
	v_max_f32_e32 v167, v167, v168
	v_cmp_lt_f32_e32 vcc, s16, v167
	s_cmp_eq_u64 vcc, 0
	s_cselect_b64 vcc, -1, 0
	v_cndmask_b32_e32 v167, v0, v166, vcc
	v_cndmask_b32_e32 v168, v2, v165, vcc
	v_sub_f32_e32 v0, v166, v167
	v_exp_f32_e32 v2, v0
	v_sub_f32_e32 v0, v165, v168
	v_exp_f32_e32 v0, v0
	v_cmp_neq_f32_e32 vcc, 1.0, v2
	v_cmp_neq_f32_e64 s[0:1], 1.0, v0
	s_or_b64 vcc, vcc, s[0:1]
	s_cbranch_vccz .LBB0_505
	v_pk_mul_f32 v[82:83], v[82:83], v[2:3] op_sel_hi:[1,0]
	v_pk_mul_f32 v[80:81], v[80:81], v[2:3] op_sel_hi:[1,0]
	v_pk_mul_f32 v[74:75], v[74:75], v[2:3] op_sel_hi:[1,0]
	v_pk_mul_f32 v[72:73], v[72:73], v[2:3] op_sel_hi:[1,0]
	v_pk_mul_f32 v[66:67], v[66:67], v[2:3] op_sel_hi:[1,0]
	v_pk_mul_f32 v[64:65], v[64:65], v[2:3] op_sel_hi:[1,0]
	v_pk_mul_f32 v[58:59], v[58:59], v[2:3] op_sel_hi:[1,0]
	v_pk_mul_f32 v[56:57], v[56:57], v[2:3] op_sel_hi:[1,0]
	v_pk_mul_f32 v[78:79], v[78:79], v[0:1] op_sel_hi:[1,0]
	v_pk_mul_f32 v[76:77], v[76:77], v[0:1] op_sel_hi:[1,0]
	v_pk_mul_f32 v[70:71], v[70:71], v[0:1] op_sel_hi:[1,0]
	v_pk_mul_f32 v[68:69], v[68:69], v[0:1] op_sel_hi:[1,0]
	v_pk_mul_f32 v[62:63], v[62:63], v[0:1] op_sel_hi:[1,0]
	v_pk_mul_f32 v[60:61], v[60:61], v[0:1] op_sel_hi:[1,0]
	v_pk_mul_f32 v[54:55], v[54:55], v[0:1] op_sel_hi:[1,0]
	v_pk_mul_f32 v[52:53], v[52:53], v[0:1] op_sel_hi:[1,0]
	v_pk_mul_f32 v[86:87], v[86:87], v[2:3] op_sel_hi:[1,0]
	v_pk_mul_f32 v[84:85], v[84:85], v[2:3] op_sel_hi:[1,0]
	v_pk_mul_f32 v[90:91], v[90:91], v[0:1] op_sel_hi:[1,0]
	v_pk_mul_f32 v[88:89], v[88:89], v[0:1] op_sel_hi:[1,0]

; DEVI void attn_item(const Params& p, int bg, int t0, unsigned char* smem) {
;     ...
;         if (is_slc && !elem) {
;             const unsigned aw = __builtin_amdgcn_readfirstlane(anyw[jt >> 5] | anyw[4 + (jt >> 5)]);
;             any_act = (aw >> (jt & 31)) & 1u;
;         }
;         if (any_act) {
;             f32x4 s[2][4];
;             {
;                 bf16x8 k0[4], k1[4];
; #pragma unroll
;                 for (int mt = 0; mt < 4; ++mt) {
;                     k0[mt] = *(const bf16x8*)(cK + (mt * 16 + l16) * 128 + ((quad ^ rsw) * 16));
;                     k1[mt] = *(const bf16x8*)(cK + (mt * 16 + l16) * 128 + (((4 + quad) ^ rsw) * 16));
;                 }
; #pragma unroll
;                 for (int mt = 0; mt < 4; ++mt)
; #pragma unroll
;                     for (int ct = 0; ct < 2; ++ct) s[ct][mt] = mfma16(k0[mt], qf[ct][0], (f32x4){0.f, 0.f, 0.f, 0.f});
; #pragma unroll
;                 for (int mt = 0; mt < 4; ++mt)
; #pragma unroll
;                     for (int ct = 0; ct < 2; ++ct) s[ct][mt] = mfma16(k1[mt], qf[ct][1], s[ct][mt]);
;     ...
; #pragma unroll
;                         for (int ct = 0; ct < 2; ++ct) {
;                             mr[ct] = fmaxf(fmaxf(s[ct][0][0], s[ct][0][1]), fmaxf(s[ct][0][2], s[ct][0][3]));
; #pragma unroll
;                             for (int mt = 1; mt < 4; ++mt) mr[ct] = fmaxf(mr[ct], fmaxf(fmaxf(s[ct][mt][0], s[ct][mt][1]), fmaxf(s[ct][mt][2], s[ct][mt][3])));
;                         }
; #pragma unroll
;                         for (int ct = 0; ct < 2; ++ct) mr[ct] = rmax16(mr[ct]);
; #pragma unroll
;                         for (int ct = 0; ct < 2; ++ct) mr[ct] = rmax32(mr[ct]);
;                         float cand[2];
;                         bool need = false;
; #pragma unroll
;                         for (int ct = 0; ct < 2; ++ct) {
;                             cand[ct] = fmaxf(m[ct], __builtin_fmaf(mr[ct], LOG2E, bias[ct]));
;                             need = need || (cand[ct] - m[ct] > 8.0f);
;                         }
;                         const bool resc = __builtin_amdgcn_ballot_w64(need) != 0;
; #pragma unroll
;                         for (int ct = 0; ct < 2; ++ct) {
;                             mn[ct] = resc ? cand[ct] : m[ct];
;                             const float nb = bias[ct] - mn[ct];
; #pragma unroll
;                             for (int mt = 0; mt < 4; ++mt)
.LBB0_651:
	s_add_i32 s0, s70, s13
	s_ashr_i32 s1, s0, 5
	s_lshl_b32 s13, s1, 2
	s_add_i32 s13, s11, s13
	v_mov_b32_e32 v0, s13
	v_add_u32_e32 v0, 0xa000, v0
	ds_read2_b32 v[92:93], v0 offset0:32 offset1:36
	s_lshl_b32 s0, 1, s0
	s_waitcnt lgkmcnt(0)
	v_or_b32_e32 v0, v93, v92
	s_nop 0
	v_readfirstlane_b32 s13, v0
	s_and_b32 s13, s13, s0
	s_cmp_eq_u32 s13, 0
	s_cbranch_scc1 .LBB0_639
	s_and_b32 s13, s71, 0x4000
	v_or_b32_e32 v171, s13, v160
	v_add_u32_e32 v0, v171, v161
	ds_read_b128 v[92:95], v0
	v_add_u32_e32 v2, v171, v162
	ds_read_b128 v[96:99], v2
	ds_read_b128 v[100:103], v0 offset:2048
	ds_read_b128 v[108:111], v2 offset:2048
	ds_read_b128 v[104:107], v0 offset:4096
	ds_read_b128 v[172:175], v2 offset:4096
	ds_read_b128 v[112:115], v0 offset:6144
	ds_read_b128 v[176:179], v2 offset:6144
	s_waitcnt vmcnt(5) lgkmcnt(3)
	v_mfma_f32_16x16x32_bf16 v[184:187], v[104:107], v[4:7], 0
	v_lshl_add_u32 v0, s1, 2, v170
	v_add_u32_e32 v0, 0xa000, v0
	s_waitcnt vmcnt(2)
	v_mfma_f32_16x16x32_bf16 v[188:191], v[104:107], v[12:15], 0
	v_mfma_f32_16x16x32_bf16 v[116:119], v[92:95], v[4:7], 0
	v_mfma_f32_16x16x32_bf16 v[92:95], v[92:95], v[12:15], 0
	s_waitcnt lgkmcnt(1)
	v_mfma_f32_16x16x32_bf16 v[192:195], v[112:115], v[4:7], 0
	v_mfma_f32_16x16x32_bf16 v[196:199], v[112:115], v[12:15], 0
	v_mfma_f32_16x16x32_bf16 v[120:123], v[96:99], v[8:11], v[116:119]
	s_waitcnt vmcnt(1)
	v_mfma_f32_16x16x32_bf16 v[104:107], v[96:99], v[16:19], v[92:95]
	v_mfma_f32_16x16x32_bf16 v[112:115], v[172:175], v[8:11], v[184:187]
	s_nop 4
	v_mfma_f32_16x16x32_bf16 v[96:99], v[172:175], v[16:19], v[188:191]
	ds_read2_b32 v[174:175], v0 offset1:16
	s_waitcnt lgkmcnt(0)
	v_and_b32_e32 v0, s0, v174
	v_mfma_f32_16x16x32_bf16 v[180:183], v[100:103], v[4:7], 0
	v_cmp_eq_u32_e32 vcc, 0, v0
	v_and_b32_e32 v0, s0, v175
	v_mfma_f32_16x16x32_bf16 v[100:103], v[100:103], v[12:15], 0
	v_cndmask_b32_e32 v173, 0, v147, vcc
	v_cmp_eq_u32_e32 vcc, 0, v0
	v_mfma_f32_16x16x32_bf16 v[116:119], v[108:111], v[8:11], v[180:183]
	v_max_f32_e32 v0, v120, v121
	v_max_f32_e32 v2, v122, v123
	v_mfma_f32_16x16x32_bf16 v[100:103], v[108:111], v[16:19], v[100:103]
	v_cndmask_b32_e32 v172, 0, v147, vcc
	s_nop 2
	v_mfma_f32_16x16x32_bf16 v[108:111], v[176:179], v[8:11], v[192:195]
	v_max_f32_e32 v167, v118, v119
	v_max3_f32 v167, v116, v117, v167
	v_max3_f32 v0, v0, v2, v167
	v_max_f32_e32 v2, v114, v115
	s_nop 1
	v_max_f32_e32 v167, v110, v111
	v_max3_f32 v2, v112, v113, v2
	v_max3_f32 v167, v108, v109, v167
	v_max3_f32 v0, v0, v2, v167
	v_max_f32_e32 v2, v104, v105
	v_mfma_f32_16x16x32_bf16 v[92:95], v[176:179], v[16:19], v[196:199]
	v_max_f32_e32 v167, v106, v107
	v_max_f32_e32 v168, v102, v103
	v_max3_f32 v168, v100, v101, v168
	v_max3_f32 v2, v2, v167, v168
	v_max_f32_e32 v167, v98, v99
	v_max_f32_e32 v174, v94, v94
	v_max_f32_e32 v168, v174, v95
	v_max3_f32 v167, v96, v97, v167
	v_max3_f32 v168, v92, v93, v168
	v_max3_f32 v2, v2, v167, v168
	v_mov_b32_e32 v167, v0
	s_nop 1
	v_permlane16_swap_b32_e32 v0, v167
	v_max_f32_e32 v167, v167, v167
	v_max_f32_e32 v0, v0, v0
	v_max_f32_e32 v0, v0, v167
	v_mov_b32_e32 v167, v2
	s_nop 1
	v_permlane16_swap_b32_e32 v2, v167
	v_max_f32_e32 v167, v167, v167
	v_max_f32_e32 v2, v2, v2
	v_max_f32_e32 v2, v2, v167
	v_mov_b32_e32 v167, v0
	s_nop 1
	v_permlane32_swap_b32_e32 v0, v167
	v_max_f32_e32 v167, v167, v167
	v_max_f32_e32 v0, v0, v0
	v_max_f32_e32 v0, v0, v167
	v_mov_b32_e32 v167, v2
	s_nop 1
	v_permlane32_swap_b32_e32 v2, v167
	v_max_f32_e32 v167, v167, v167
	v_max_f32_e32 v2, v2, v2
	v_max_f32_e32 v2, v2, v167
	v_fmamk_f32 v0, v0, 0x3fb8aa3b, v173
	v_fmamk_f32 v2, v2, 0x3fb8aa3b, v172
	v_max_f32_e32 v0, v166, v0
	v_max_f32_e32 v2, v165, v2
	v_sub_f32_e32 v167, v0, v166
	v_sub_f32_e32 v168, v2, v165
	v_max_f32_e32 v167, v167, v168
	v_cmp_lt_f32_e32 vcc, s16, v167
	s_cmp_eq_u64 vcc, 0
	s_cselect_b64 vcc, -1, 0
	v_cndmask_b32_e32 v167, v0, v166, vcc
	v_cndmask_b32_e32 v168, v2, v165, vcc
	v_sub_f32_e32 v0, v166, v167
	v_exp_f32_e32 v2, v0
	v_sub_f32_e32 v0, v165, v168
	v_exp_f32_e32 v0, v0
	v_cmp_neq_f32_e32 vcc, 1.0, v2
	v_cmp_neq_f32_e64 s[0:1], 1.0, v0
	s_or_b64 vcc, vcc, s[0:1]
	s_cbranch_vccz .LBB0_654
	v_pk_mul_f32 v[82:83], v[82:83], v[2:3] op_sel_hi:[1,0]
	v_pk_mul_f32 v[80:81], v[80:81], v[2:3] op_sel_hi:[1,0]
	v_pk_mul_f32 v[74:75], v[74:75], v[2:3] op_sel_hi:[1,0]
	v_pk_mul_f32 v[72:73], v[72:73], v[2:3] op_sel_hi:[1,0]
	v_pk_mul_f32 v[66:67], v[66:67], v[2:3] op_sel_hi:[1,0]
	v_pk_mul_f32 v[64:65], v[64:65], v[2:3] op_sel_hi:[1,0]
	v_pk_mul_f32 v[58:59], v[58:59], v[2:3] op_sel_hi:[1,0]
	v_pk_mul_f32 v[56:57], v[56:57], v[2:3] op_sel_hi:[1,0]
	v_pk_mul_f32 v[78:79], v[78:79], v[0:1] op_sel_hi:[1,0]
	v_pk_mul_f32 v[76:77], v[76:77], v[0:1] op_sel_hi:[1,0]
	v_pk_mul_f32 v[70:71], v[70:71], v[0:1] op_sel_hi:[1,0]
	v_pk_mul_f32 v[68:69], v[68:69], v[0:1] op_sel_hi:[1,0]
	v_pk_mul_f32 v[62:63], v[62:63], v[0:1] op_sel_hi:[1,0]
	v_pk_mul_f32 v[60:61], v[60:61], v[0:1] op_sel_hi:[1,0]
	v_pk_mul_f32 v[54:55], v[54:55], v[0:1] op_sel_hi:[1,0]
	v_pk_mul_f32 v[52:53], v[52:53], v[0:1] op_sel_hi:[1,0]
	v_pk_mul_f32 v[86:87], v[86:87], v[2:3] op_sel_hi:[1,0]
	v_pk_mul_f32 v[84:85], v[84:85], v[2:3] op_sel_hi:[1,0]
	v_pk_mul_f32 v[90:91], v[90:91], v[0:1] op_sel_hi:[1,0]
	v_pk_mul_f32 v[88:89], v[88:89], v[0:1] op_sel_hi:[1,0]
